# m26 + XCD leaders no longer issue (and wait for) the XGEN release atomic: every CU leaves the barrier on the TOPGEN flip
# speedup vs baseline: 1.0012x; 1.0012x over previous
; __device__ __forceinline__ unsigned xb_add(unsigned* p, unsigned v) { return __hip_atomic_fetch_add(p, v, __ATOMIC_RELAXED, __HIP_MEMORY_SCOPE_AGENT); }
; __device__ __forceinline__ void xcd_barrier(const XcdBarrier& b) {
;     ...
;             __builtin_amdgcn_fence(__ATOMIC_ACQUIRE, "agent");
;             xb_add(&bar[XB_XGEN(b.x)], 1u);
;             asm volatile("s_waitcnt vmcnt(0)" ::: "memory");
.LBB11_443:
	s_or_b64 exec, exec, s[6:7]
	s_mov_b64 s[6:7], exec
	v_mbcnt_lo_u32_b32 v1, s6, 0
	v_mbcnt_hi_u32_b32 v1, s7, v1
	v_cmp_eq_u32_e32 vcc, 0, v1
	s_waitcnt vmcnt(0)
	s_and_saveexec_b64 s[8:9], vcc
	s_cbranch_execz .LBB11_445
	s_bcnt1_i32_b64 s1, s[6:7]
	v_readlane_b32 s6, v250, 47
	v_mov_b32_e32 v1, s1
	v_readlane_b32 s7, v250, 48
	s_nop 4
.LBB11_445:
	s_or_b64 exec, exec, s[8:9]
	s_waitcnt vmcnt(0)

; __device__ __forceinline__ unsigned xb_add(unsigned* p, unsigned v) { return __hip_atomic_fetch_add(p, v, __ATOMIC_RELAXED, __HIP_MEMORY_SCOPE_AGENT); }
; __device__ __forceinline__ void xcd_barrier(const XcdBarrier& b) {
;     ...
;             __builtin_amdgcn_fence(__ATOMIC_ACQUIRE, "agent");
;             xb_add(&bar[XB_XGEN(b.x)], 1u);
;             asm volatile("s_waitcnt vmcnt(0)" ::: "memory");
.LBB11_621:
	s_or_b64 exec, exec, s[4:5]
	s_mov_b64 s[4:5], exec
	v_mbcnt_lo_u32_b32 v1, s4, 0
	v_mbcnt_hi_u32_b32 v1, s5, v1
	v_cmp_eq_u32_e32 vcc, 0, v1
	s_waitcnt vmcnt(0)
	s_and_saveexec_b64 s[8:9], vcc
	s_cbranch_execz .LBB11_623
	s_bcnt1_i32_b64 s1, s[4:5]
	v_readlane_b32 s4, v250, 47
	v_mov_b32_e32 v1, s1
	v_readlane_b32 s5, v250, 48
	s_nop 4
.LBB11_623:
	s_or_b64 exec, exec, s[8:9]
	s_waitcnt vmcnt(0)

; __device__ __forceinline__ unsigned xb_add(unsigned* p, unsigned v) { return __hip_atomic_fetch_add(p, v, __ATOMIC_RELAXED, __HIP_MEMORY_SCOPE_AGENT); }
; __device__ __forceinline__ void xcd_barrier(const XcdBarrier& b) {
;     ...
;             __builtin_amdgcn_fence(__ATOMIC_ACQUIRE, "agent");
;             xb_add(&bar[XB_XGEN(b.x)], 1u);
;             asm volatile("s_waitcnt vmcnt(0)" ::: "memory");
.LBB11_819:
	s_or_b64 exec, exec, s[4:5]
	s_mov_b64 s[4:5], exec
	v_mbcnt_lo_u32_b32 v1, s4, 0
	v_mbcnt_hi_u32_b32 v1, s5, v1
	v_cmp_eq_u32_e32 vcc, 0, v1
	s_waitcnt vmcnt(0)
	s_and_saveexec_b64 s[8:9], vcc
	s_cbranch_execz .LBB11_821
	s_bcnt1_i32_b64 s1, s[4:5]
	v_readlane_b32 s4, v250, 47
	v_mov_b32_e32 v1, s1
	v_readlane_b32 s5, v250, 48
	s_nop 4
.LBB11_821:
	s_or_b64 exec, exec, s[8:9]
	s_waitcnt vmcnt(0)

; __device__ __forceinline__ unsigned xb_add(unsigned* p, unsigned v) { return __hip_atomic_fetch_add(p, v, __ATOMIC_RELAXED, __HIP_MEMORY_SCOPE_AGENT); }
; __device__ __forceinline__ void xcd_barrier(const XcdBarrier& b) {
;     ...
;             __builtin_amdgcn_fence(__ATOMIC_ACQUIRE, "agent");
;             xb_add(&bar[XB_XGEN(b.x)], 1u);
;             asm volatile("s_waitcnt vmcnt(0)" ::: "memory");
.LBB11_900:
	s_or_b64 exec, exec, s[4:5]
	s_mov_b64 s[4:5], exec
	v_mbcnt_lo_u32_b32 v1, s4, 0
	v_mbcnt_hi_u32_b32 v1, s5, v1
	v_cmp_eq_u32_e32 vcc, 0, v1
	s_waitcnt vmcnt(0)
	s_and_saveexec_b64 s[6:7], vcc
	s_cbranch_execz .LBB11_902
	s_bcnt1_i32_b64 s1, s[4:5]
	v_readlane_b32 s4, v250, 47
	v_mov_b32_e32 v1, s1
	v_readlane_b32 s5, v250, 48
	s_nop 4
.LBB11_902:
	s_or_b64 exec, exec, s[6:7]
	s_waitcnt vmcnt(0)

; __device__ __forceinline__ unsigned xb_add(unsigned* p, unsigned v) { return __hip_atomic_fetch_add(p, v, __ATOMIC_RELAXED, __HIP_MEMORY_SCOPE_AGENT); }
; __device__ __forceinline__ void xcd_barrier(const XcdBarrier& b) {
;     ...
;             __builtin_amdgcn_fence(__ATOMIC_ACQUIRE, "agent");
;             xb_add(&bar[XB_XGEN(b.x)], 1u);
;             asm volatile("s_waitcnt vmcnt(0)" ::: "memory");
.LBB11_972:
	s_or_b64 exec, exec, s[4:5]
	s_mov_b64 s[4:5], exec
	v_mbcnt_lo_u32_b32 v1, s4, 0
	v_mbcnt_hi_u32_b32 v1, s5, v1
	v_cmp_eq_u32_e32 vcc, 0, v1
	s_waitcnt vmcnt(0)
	s_and_saveexec_b64 s[6:7], vcc
	s_cbranch_execz .LBB11_974
	s_bcnt1_i32_b64 s1, s[4:5]
	v_readlane_b32 s4, v250, 47
	v_mov_b32_e32 v1, s1
	v_readlane_b32 s5, v250, 48
	s_nop 4
.LBB11_974:
	s_or_b64 exec, exec, s[6:7]
	s_waitcnt vmcnt(0)

; __device__ __forceinline__ unsigned xb_add(unsigned* p, unsigned v) { return __hip_atomic_fetch_add(p, v, __ATOMIC_RELAXED, __HIP_MEMORY_SCOPE_AGENT); }
; __device__ __forceinline__ void xcd_barrier(const XcdBarrier& b) {
;     ...
;             __builtin_amdgcn_fence(__ATOMIC_ACQUIRE, "agent");
;             xb_add(&bar[XB_XGEN(b.x)], 1u);
;             asm volatile("s_waitcnt vmcnt(0)" ::: "memory");
.LBB11_1058:
	s_or_b64 exec, exec, s[4:5]
	s_mov_b64 s[4:5], exec
	v_mbcnt_lo_u32_b32 v1, s4, 0
	v_mbcnt_hi_u32_b32 v1, s5, v1
	v_cmp_eq_u32_e32 vcc, 0, v1
	s_waitcnt vmcnt(0)
	s_and_saveexec_b64 s[6:7], vcc
	s_cbranch_execz .LBB11_1060
	s_bcnt1_i32_b64 s1, s[4:5]
	v_readlane_b32 s4, v250, 47
	v_mov_b32_e32 v1, s1
	v_readlane_b32 s5, v250, 48
	s_nop 4
.LBB11_1060:
	s_or_b64 exec, exec, s[6:7]
	s_waitcnt vmcnt(0)

; __device__ __forceinline__ unsigned xb_add(unsigned* p, unsigned v) { return __hip_atomic_fetch_add(p, v, __ATOMIC_RELAXED, __HIP_MEMORY_SCOPE_AGENT); }
; __device__ __forceinline__ void xcd_barrier(const XcdBarrier& b) {
;     ...
;             __builtin_amdgcn_fence(__ATOMIC_ACQUIRE, "agent");
;             xb_add(&bar[XB_XGEN(b.x)], 1u);
;             asm volatile("s_waitcnt vmcnt(0)" ::: "memory");
.LBB11_1263:
	s_or_b64 exec, exec, s[4:5]
	s_mov_b64 s[4:5], exec
	v_mbcnt_lo_u32_b32 v1, s4, 0
	v_mbcnt_hi_u32_b32 v1, s5, v1
	v_cmp_eq_u32_e32 vcc, 0, v1
	s_waitcnt vmcnt(0)
	s_and_saveexec_b64 s[6:7], vcc
	s_cbranch_execz .LBB11_1265
	s_bcnt1_i32_b64 s1, s[4:5]
	v_readlane_b32 s4, v250, 47
	v_mov_b32_e32 v1, s1
	v_readlane_b32 s5, v250, 48
	s_nop 4
.LBB11_1265:
	s_or_b64 exec, exec, s[6:7]
	s_waitcnt vmcnt(0)

; __device__ __forceinline__ unsigned xb_add(unsigned* p, unsigned v) { return __hip_atomic_fetch_add(p, v, __ATOMIC_RELAXED, __HIP_MEMORY_SCOPE_AGENT); }
; __device__ __forceinline__ void xcd_barrier(const XcdBarrier& b) {
;     ...
;             __builtin_amdgcn_fence(__ATOMIC_ACQUIRE, "agent");
;             xb_add(&bar[XB_XGEN(b.x)], 1u);
;             asm volatile("s_waitcnt vmcnt(0)" ::: "memory");
.LBB11_1876:
	s_or_b64 exec, exec, s[4:5]
	s_mov_b64 s[4:5], exec
	v_mbcnt_lo_u32_b32 v1, s4, 0
	v_mbcnt_hi_u32_b32 v1, s5, v1
	v_cmp_eq_u32_e32 vcc, 0, v1
	s_waitcnt vmcnt(0)
	s_and_saveexec_b64 s[14:15], vcc
	s_cbranch_execz .LBB11_1878
	s_bcnt1_i32_b64 s1, s[4:5]
	v_readlane_b32 s4, v250, 47
	v_mov_b32_e32 v1, s1
	v_readlane_b32 s5, v250, 48
	s_nop 4
.LBB11_1878:
	s_or_b64 exec, exec, s[14:15]
	s_waitcnt vmcnt(0)
